# K-loop head SALU block (tile pointer selects) moved behind the first load segment's ds_read and DMA issue; loop tail unchanged
# speedup vs baseline: 1.0099x; 1.0099x over previous
.LBB0_405:
	ds_read_b128 v[0:3], v253
	ds_read_b128 v[4:7], v253 offset:1024
	ds_read_b128 v[138:141], v253 offset:2048
	ds_read_b128 v[142:145], v253 offset:3072
	ds_read_b128 v[146:149], v253 offset:16384
	ds_read_b128 v[150:153], v253 offset:17408
	ds_read_b128 v[180:183], v253 offset:18432
	ds_read_b128 v[184:187], v253 offset:19456
	s_add_i32 m0, s69, 0xc000
	ds_read_b128 v[188:191], v231
	ds_read_b128 v[192:195], v231 offset:1024
	ds_read_b128 v[196:199], v231 offset:2048
	ds_read_b128 v[200:203], v231 offset:3072
	ds_read_b128 v[204:207], v231 offset:4096
	ds_read_b128 v[234:237], v231 offset:5120
	ds_read_b128 v[238:241], v231 offset:6144
	ds_read_b128 v[242:245], v231 offset:7168
	global_load_lds_dwordx4 v166, s[2:3]
	s_add_i32 m0, s69, 0xe000
	s_nop 0
	global_load_lds_dwordx4 v168, s[2:3]
	s_add_u32 s12, s2, 0xfffc0080
	s_addc_u32 s13, s3, -1
	s_add_i32 s23, 0, 0x10000
	s_cmp_eq_u32 s22, 12
	s_cselect_b32 s15, s16, s13
	s_cselect_b32 s14, s17, s12
	s_cselect_b32 s13, s18, s21
	s_cselect_b32 s12, s19, s20
	s_add_i32 s31, 0, 0x14000
	s_waitcnt vmcnt(8)
	s_waitcnt lgkmcnt(0)
	s_barrier
	s_setprio 1
	s_waitcnt lgkmcnt(0)
	v_mfma_f32_16x16x32_bf16 v[134:137], v[0:3], v[188:191], v[134:137]
	v_mfma_f32_16x16x32_bf16 v[130:133], v[138:141], v[188:191], v[130:133]
	v_mfma_f32_16x16x32_bf16 v[118:121], v[0:3], v[196:199], v[118:121]
	v_mfma_f32_16x16x32_bf16 v[114:117], v[138:141], v[196:199], v[114:117]
	v_mfma_f32_16x16x32_bf16 v[102:105], v[0:3], v[204:207], v[102:105]
	v_mfma_f32_16x16x32_bf16 v[98:101], v[138:141], v[204:207], v[98:101]
	v_mfma_f32_16x16x32_bf16 v[84:87], v[0:3], v[238:241], v[84:87]
	v_mfma_f32_16x16x32_bf16 v[80:83], v[138:141], v[238:241], v[80:83]
	v_mfma_f32_16x16x32_bf16 v[134:137], v[4:7], v[192:195], v[134:137]
	v_mfma_f32_16x16x32_bf16 v[130:133], v[142:145], v[192:195], v[130:133]
	v_mfma_f32_16x16x32_bf16 v[118:121], v[4:7], v[200:203], v[118:121]
	v_mfma_f32_16x16x32_bf16 v[114:117], v[142:145], v[200:203], v[114:117]
	v_mfma_f32_16x16x32_bf16 v[102:105], v[4:7], v[234:237], v[102:105]
	v_mfma_f32_16x16x32_bf16 v[98:101], v[142:145], v[234:237], v[98:101]
	v_mfma_f32_16x16x32_bf16 v[84:87], v[4:7], v[242:245], v[84:87]
	v_mfma_f32_16x16x32_bf16 v[80:83], v[142:145], v[242:245], v[80:83]
	s_setprio 0
	s_setprio 1
	v_mfma_f32_16x16x32_bf16 v[126:129], v[146:149], v[188:191], v[126:129]
	v_mfma_f32_16x16x32_bf16 v[122:125], v[180:183], v[188:191], v[122:125]
	v_mfma_f32_16x16x32_bf16 v[110:113], v[146:149], v[196:199], v[110:113]
	v_mfma_f32_16x16x32_bf16 v[106:109], v[180:183], v[196:199], v[106:109]
	v_mfma_f32_16x16x32_bf16 v[92:95], v[146:149], v[204:207], v[92:95]
	v_mfma_f32_16x16x32_bf16 v[88:91], v[180:183], v[204:207], v[88:91]
	v_mfma_f32_16x16x32_bf16 v[76:79], v[146:149], v[238:241], v[76:79]
	v_mfma_f32_16x16x32_bf16 v[72:75], v[180:183], v[238:241], v[72:75]
	v_mfma_f32_16x16x32_bf16 v[126:129], v[150:153], v[192:195], v[126:129]
	v_mfma_f32_16x16x32_bf16 v[122:125], v[184:187], v[192:195], v[122:125]
	v_mfma_f32_16x16x32_bf16 v[110:113], v[150:153], v[200:203], v[110:113]
	v_mfma_f32_16x16x32_bf16 v[106:109], v[184:187], v[200:203], v[106:109]
	v_mfma_f32_16x16x32_bf16 v[92:95], v[150:153], v[234:237], v[92:95]
	v_mfma_f32_16x16x32_bf16 v[88:91], v[184:187], v[234:237], v[88:91]
	v_mfma_f32_16x16x32_bf16 v[76:79], v[150:153], v[242:245], v[76:79]
	v_mfma_f32_16x16x32_bf16 v[72:75], v[184:187], v[242:245], v[72:75]
	s_setprio 0
	s_barrier
	s_add_i32 s23, s23, s58
	s_mov_b32 m0, s23
	ds_read_b128 v[188:191], v231 offset:16384
	ds_read_b128 v[192:195], v231 offset:17408
	ds_read_b128 v[196:199], v231 offset:18432
	ds_read_b128 v[200:203], v231 offset:19456
	ds_read_b128 v[204:207], v231 offset:20480
	ds_read_b128 v[234:237], v231 offset:21504
	ds_read_b128 v[238:241], v231 offset:22528
	ds_read_b128 v[242:245], v231 offset:23552
	global_load_lds_dwordx4 v156, s[12:13]
	s_add_i32 m0, s23, 0x2000
	s_add_u32 s26, s12, 0x10000
	s_addc_u32 s27, s13, 0
	s_add_i32 s23, s31, s58
	global_load_lds_dwordx4 v160, s[12:13]
	s_mov_b32 m0, s23
	s_nop 0
	global_load_lds_dwordx4 v156, s[26:27]
	s_add_i32 m0, s23, 0x2000
	s_nop 0
	global_load_lds_dwordx4 v160, s[26:27]
	s_mov_b64 s[26:27], s[14:15]
	s_mov_b32 m0, s69
	s_nop 0
	global_load_lds_dwordx4 v154, s[14:15]
	s_mov_b32 m0, s70
	s_nop 0
	global_load_lds_dwordx4 v158, s[14:15]
	s_waitcnt vmcnt(8)
	s_waitcnt lgkmcnt(0)
	s_barrier
	s_setprio 1
	s_waitcnt lgkmcnt(0)
	v_mfma_f32_16x16x32_bf16 v[68:71], v[0:3], v[188:191], v[68:71]
	v_mfma_f32_16x16x32_bf16 v[64:67], v[138:141], v[188:191], v[64:67]
	v_mfma_f32_16x16x32_bf16 v[52:55], v[0:3], v[196:199], v[52:55]
	v_mfma_f32_16x16x32_bf16 v[48:51], v[138:141], v[196:199], v[48:51]
	v_mfma_f32_16x16x32_bf16 v[36:39], v[0:3], v[204:207], v[36:39]
	v_mfma_f32_16x16x32_bf16 v[32:35], v[138:141], v[204:207], v[32:35]
	v_mfma_f32_16x16x32_bf16 v[0:3], v[0:3], v[238:241], v[20:23]
	v_mfma_f32_16x16x32_bf16 v[68:71], v[4:7], v[192:195], v[68:71]
	v_mfma_f32_16x16x32_bf16 v[64:67], v[142:145], v[192:195], v[64:67]
	v_mfma_f32_16x16x32_bf16 v[52:55], v[4:7], v[200:203], v[52:55]
	v_mfma_f32_16x16x32_bf16 v[48:51], v[142:145], v[200:203], v[48:51]
	v_mfma_f32_16x16x32_bf16 v[36:39], v[4:7], v[234:237], v[36:39]
	v_mfma_f32_16x16x32_bf16 v[32:35], v[142:145], v[234:237], v[32:35]
	v_mfma_f32_16x16x32_bf16 v[0:3], v[4:7], v[242:245], v[0:3]
	v_mfma_f32_16x16x32_bf16 v[4:7], v[138:141], v[238:241], v[16:19]
	v_mfma_f32_16x16x32_bf16 v[4:7], v[142:145], v[242:245], v[4:7]
	s_setprio 0
	s_setprio 1
	v_mfma_f32_16x16x32_bf16 v[16:19], v[146:149], v[188:191], v[60:63]
	v_mfma_f32_16x16x32_bf16 v[60:63], v[150:153], v[192:195], v[16:19]
	v_mfma_f32_16x16x32_bf16 v[16:19], v[180:183], v[188:191], v[56:59]
	v_mfma_f32_16x16x32_bf16 v[56:59], v[184:187], v[192:195], v[16:19]
	v_mfma_f32_16x16x32_bf16 v[16:19], v[146:149], v[196:199], v[44:47]
	v_mfma_f32_16x16x32_bf16 v[44:47], v[150:153], v[200:203], v[16:19]
	v_mfma_f32_16x16x32_bf16 v[16:19], v[180:183], v[196:199], v[40:43]
	v_mfma_f32_16x16x32_bf16 v[40:43], v[184:187], v[200:203], v[16:19]
	v_mfma_f32_16x16x32_bf16 v[16:19], v[146:149], v[204:207], v[28:31]
	v_mfma_f32_16x16x32_bf16 v[28:31], v[150:153], v[234:237], v[16:19]
	v_mfma_f32_16x16x32_bf16 v[16:19], v[180:183], v[204:207], v[24:27]
	v_mfma_f32_16x16x32_bf16 v[12:15], v[146:149], v[238:241], v[12:15]
	v_mfma_f32_16x16x32_bf16 v[8:11], v[180:183], v[238:241], v[8:11]
	v_mfma_f32_16x16x32_bf16 v[24:27], v[184:187], v[234:237], v[16:19]
	v_mfma_f32_16x16x32_bf16 v[12:15], v[150:153], v[242:245], v[12:15]
	v_mfma_f32_16x16x32_bf16 v[8:11], v[184:187], v[242:245], v[8:11]
	s_setprio 0
	s_barrier
	s_add_i32 s23, 0, 0x1c000
	ds_read_b128 v[16:19], v253 offset:32768
	ds_read_b128 v[20:23], v253 offset:33792
	ds_read_b128 v[138:141], v253 offset:34816
	ds_read_b128 v[142:145], v253 offset:35840
	ds_read_b128 v[146:149], v253 offset:49152
	ds_read_b128 v[150:153], v253 offset:50176
	ds_read_b128 v[180:183], v253 offset:51200
	ds_read_b128 v[184:187], v253 offset:52224
	s_add_u32 s14, s14, 0x40000
	s_addc_u32 s15, s15, 0
	s_mov_b32 m0, s71
	ds_read_b128 v[188:191], v231 offset:32768
	ds_read_b128 v[192:195], v231 offset:33792
	ds_read_b128 v[196:199], v231 offset:34816
	ds_read_b128 v[200:203], v231 offset:35840
	ds_read_b128 v[204:207], v231 offset:36864
	ds_read_b128 v[234:237], v231 offset:37888
	ds_read_b128 v[238:241], v231 offset:38912
	ds_read_b128 v[242:245], v231 offset:39936
	global_load_lds_dwordx4 v154, s[14:15]
	s_mov_b32 m0, s76
	s_nop 0
	global_load_lds_dwordx4 v158, s[14:15]
	s_waitcnt vmcnt(8)
	s_waitcnt lgkmcnt(0)
	s_barrier
	s_setprio 1
	s_waitcnt lgkmcnt(0)
	v_mfma_f32_16x16x32_bf16 v[134:137], v[16:19], v[188:191], v[134:137]
	v_mfma_f32_16x16x32_bf16 v[130:133], v[138:141], v[188:191], v[130:133]
	v_mfma_f32_16x16x32_bf16 v[118:121], v[16:19], v[196:199], v[118:121]
	v_mfma_f32_16x16x32_bf16 v[114:117], v[138:141], v[196:199], v[114:117]
	v_mfma_f32_16x16x32_bf16 v[102:105], v[16:19], v[204:207], v[102:105]
	v_mfma_f32_16x16x32_bf16 v[98:101], v[138:141], v[204:207], v[98:101]
	v_mfma_f32_16x16x32_bf16 v[84:87], v[16:19], v[238:241], v[84:87]
	v_mfma_f32_16x16x32_bf16 v[80:83], v[138:141], v[238:241], v[80:83]
	v_mfma_f32_16x16x32_bf16 v[134:137], v[20:23], v[192:195], v[134:137]
	v_mfma_f32_16x16x32_bf16 v[130:133], v[142:145], v[192:195], v[130:133]
	v_mfma_f32_16x16x32_bf16 v[118:121], v[20:23], v[200:203], v[118:121]
	v_mfma_f32_16x16x32_bf16 v[114:117], v[142:145], v[200:203], v[114:117]
	v_mfma_f32_16x16x32_bf16 v[102:105], v[20:23], v[234:237], v[102:105]
	v_mfma_f32_16x16x32_bf16 v[98:101], v[142:145], v[234:237], v[98:101]
	v_mfma_f32_16x16x32_bf16 v[84:87], v[20:23], v[242:245], v[84:87]
	v_mfma_f32_16x16x32_bf16 v[80:83], v[142:145], v[242:245], v[80:83]
	s_setprio 0
	s_setprio 1
	v_mfma_f32_16x16x32_bf16 v[126:129], v[146:149], v[188:191], v[126:129]
	v_mfma_f32_16x16x32_bf16 v[122:125], v[180:183], v[188:191], v[122:125]
	v_mfma_f32_16x16x32_bf16 v[110:113], v[146:149], v[196:199], v[110:113]
	v_mfma_f32_16x16x32_bf16 v[106:109], v[180:183], v[196:199], v[106:109]
	v_mfma_f32_16x16x32_bf16 v[92:95], v[146:149], v[204:207], v[92:95]
	v_mfma_f32_16x16x32_bf16 v[88:91], v[180:183], v[204:207], v[88:91]
	v_mfma_f32_16x16x32_bf16 v[76:79], v[146:149], v[238:241], v[76:79]
	v_mfma_f32_16x16x32_bf16 v[72:75], v[180:183], v[238:241], v[72:75]
	v_mfma_f32_16x16x32_bf16 v[126:129], v[150:153], v[192:195], v[126:129]
	v_mfma_f32_16x16x32_bf16 v[122:125], v[184:187], v[192:195], v[122:125]
	v_mfma_f32_16x16x32_bf16 v[110:113], v[150:153], v[200:203], v[110:113]
	v_mfma_f32_16x16x32_bf16 v[106:109], v[184:187], v[200:203], v[106:109]
	v_mfma_f32_16x16x32_bf16 v[92:95], v[150:153], v[234:237], v[92:95]
	v_mfma_f32_16x16x32_bf16 v[88:91], v[184:187], v[234:237], v[88:91]
	v_mfma_f32_16x16x32_bf16 v[76:79], v[150:153], v[242:245], v[76:79]
	v_mfma_f32_16x16x32_bf16 v[72:75], v[184:187], v[242:245], v[72:75]
	s_setprio 0
	s_barrier
	s_add_i32 s14, s67, s58
	s_add_i32 m0, s14, 0xffffff80
	ds_read_b128 v[188:191], v231 offset:49152
	ds_read_b128 v[192:195], v231 offset:50176
	ds_read_b128 v[196:199], v231 offset:51200
	ds_read_b128 v[200:203], v231 offset:52224
	ds_read_b128 v[204:207], v231 offset:53248
	ds_read_b128 v[234:237], v231 offset:54272
	ds_read_b128 v[238:241], v231 offset:55296
	ds_read_b128 v[242:245], v231 offset:56320
	global_load_lds_dwordx4 v156, s[12:13] offset:128
	s_add_i32 m0, s14, 0x1f80
	s_add_i32 s14, s23, s58
	global_load_lds_dwordx4 v160, s[12:13] offset:128
	s_add_u32 s12, s12, 0x10080
	s_addc_u32 s13, s13, 0
	s_mov_b32 m0, s14
	s_nop 0
	global_load_lds_dwordx4 v156, s[12:13]
	s_add_i32 m0, s14, 0x2000
	s_nop 0
	global_load_lds_dwordx4 v160, s[12:13]
	s_add_i32 m0, s96, 0xffffff80
	s_nop 0
	global_load_lds_dwordx4 v154, s[26:27] offset:128
	s_add_i32 m0, s36, 0xffffff80
	s_nop 0
	global_load_lds_dwordx4 v158, s[26:27] offset:128
	s_waitcnt vmcnt(8)
	s_waitcnt lgkmcnt(0)
	s_barrier
	s_setprio 1
	s_waitcnt lgkmcnt(0)
	v_mfma_f32_16x16x32_bf16 v[68:71], v[16:19], v[188:191], v[68:71]
	v_mfma_f32_16x16x32_bf16 v[52:55], v[16:19], v[196:199], v[52:55]
	v_mfma_f32_16x16x32_bf16 v[36:39], v[16:19], v[204:207], v[36:39]
	v_mfma_f32_16x16x32_bf16 v[0:3], v[16:19], v[238:241], v[0:3]
	v_mfma_f32_16x16x32_bf16 v[68:71], v[20:23], v[192:195], v[68:71]
	v_mfma_f32_16x16x32_bf16 v[64:67], v[138:141], v[188:191], v[64:67]
	v_mfma_f32_16x16x32_bf16 v[52:55], v[20:23], v[200:203], v[52:55]
	v_mfma_f32_16x16x32_bf16 v[48:51], v[138:141], v[196:199], v[48:51]
	v_mfma_f32_16x16x32_bf16 v[36:39], v[20:23], v[234:237], v[36:39]
	v_mfma_f32_16x16x32_bf16 v[32:35], v[138:141], v[204:207], v[32:35]
	v_mfma_f32_16x16x32_bf16 v[20:23], v[20:23], v[242:245], v[0:3]
	v_mfma_f32_16x16x32_bf16 v[0:3], v[138:141], v[238:241], v[4:7]
	v_mfma_f32_16x16x32_bf16 v[64:67], v[142:145], v[192:195], v[64:67]
	v_mfma_f32_16x16x32_bf16 v[48:51], v[142:145], v[200:203], v[48:51]
	v_mfma_f32_16x16x32_bf16 v[32:35], v[142:145], v[234:237], v[32:35]
	v_mfma_f32_16x16x32_bf16 v[16:19], v[142:145], v[242:245], v[0:3]
	s_setprio 0
	s_setprio 1
	v_mfma_f32_16x16x32_bf16 v[0:3], v[146:149], v[188:191], v[60:63]
	v_mfma_f32_16x16x32_bf16 v[60:63], v[150:153], v[192:195], v[0:3]
	v_mfma_f32_16x16x32_bf16 v[0:3], v[180:183], v[188:191], v[56:59]
	v_mfma_f32_16x16x32_bf16 v[56:59], v[184:187], v[192:195], v[0:3]
	v_mfma_f32_16x16x32_bf16 v[0:3], v[146:149], v[196:199], v[44:47]
	v_mfma_f32_16x16x32_bf16 v[44:47], v[150:153], v[200:203], v[0:3]
	v_mfma_f32_16x16x32_bf16 v[0:3], v[180:183], v[196:199], v[40:43]
	v_mfma_f32_16x16x32_bf16 v[40:43], v[184:187], v[200:203], v[0:3]
	v_mfma_f32_16x16x32_bf16 v[0:3], v[146:149], v[204:207], v[28:31]
	v_mfma_f32_16x16x32_bf16 v[28:31], v[150:153], v[234:237], v[0:3]
	v_mfma_f32_16x16x32_bf16 v[0:3], v[180:183], v[204:207], v[24:27]
	v_mfma_f32_16x16x32_bf16 v[24:27], v[184:187], v[234:237], v[0:3]
	v_mfma_f32_16x16x32_bf16 v[0:3], v[146:149], v[238:241], v[12:15]
	v_mfma_f32_16x16x32_bf16 v[12:15], v[150:153], v[242:245], v[0:3]
	v_mfma_f32_16x16x32_bf16 v[0:3], v[180:183], v[238:241], v[8:11]
	v_mfma_f32_16x16x32_bf16 v[8:11], v[184:187], v[242:245], v[0:3]
	s_setprio 0
	s_barrier
	s_add_i32 s22, s22, 2
	s_add_u32 s2, s2, 0x100
	s_addc_u32 s3, s3, 0
	s_add_u32 s20, s20, 0x100
	s_addc_u32 s21, s21, 0
	s_cmp_gt_u32 s22, 13
	s_cbranch_scc0 .LBB0_405
	s_and_b64 vcc, exec, s[42:43]
	s_cbranch_vccz .LBB0_418
	s_barrier
	s_andn2_b64 vcc, exec, s[38:39]
	s_mov_b64 s[2:3], -1
	s_cbranch_vccz .LBB0_419

.LBB0_750:
	ds_read_b128 v[0:3], v253
	ds_read_b128 v[4:7], v253 offset:1024
	ds_read_b128 v[138:141], v253 offset:2048
	ds_read_b128 v[142:145], v253 offset:3072
	ds_read_b128 v[146:149], v253 offset:16384
	ds_read_b128 v[150:153], v253 offset:17408
	ds_read_b128 v[182:185], v253 offset:18432
	ds_read_b128 v[186:189], v253 offset:19456
	s_add_i32 m0, s79, 0xc000
	ds_read_b128 v[190:193], v221
	ds_read_b128 v[194:197], v221 offset:1024
	ds_read_b128 v[198:201], v221 offset:2048
	ds_read_b128 v[202:205], v221 offset:3072
	ds_read_b128 v[222:225], v221 offset:4096
	ds_read_b128 v[226:229], v221 offset:5120
	ds_read_b128 v[230:233], v221 offset:6144
	ds_read_b128 v[234:237], v221 offset:7168
	global_load_lds_dwordx4 v168, s[4:5]
	s_add_i32 m0, s79, 0xe000
	s_nop 0
	global_load_lds_dwordx4 v170, s[4:5]
	s_add_u32 s12, s4, 0xfffc0080
	s_addc_u32 s13, s5, -1
	s_add_i32 s33, 0, 0x10000
	s_cmp_eq_u32 s27, 12
	s_cselect_b32 s15, s3, s13
	s_cselect_b32 s14, s16, s12
	s_cselect_b32 s13, s17, s26
	s_cselect_b32 s12, s18, s19
	s_add_i32 s35, 0, 0x14000
	s_waitcnt vmcnt(8)
	s_waitcnt lgkmcnt(0)
	s_barrier
	s_setprio 1
	s_waitcnt lgkmcnt(0)
	v_mfma_f32_16x16x32_bf16 v[134:137], v[0:3], v[190:193], v[134:137]
	v_mfma_f32_16x16x32_bf16 v[130:133], v[138:141], v[190:193], v[130:133]
	v_mfma_f32_16x16x32_bf16 v[118:121], v[0:3], v[198:201], v[118:121]
	v_mfma_f32_16x16x32_bf16 v[114:117], v[138:141], v[198:201], v[114:117]
	v_mfma_f32_16x16x32_bf16 v[102:105], v[0:3], v[222:225], v[102:105]
	v_mfma_f32_16x16x32_bf16 v[98:101], v[138:141], v[222:225], v[98:101]
	v_mfma_f32_16x16x32_bf16 v[84:87], v[0:3], v[230:233], v[84:87]
	v_mfma_f32_16x16x32_bf16 v[80:83], v[138:141], v[230:233], v[80:83]
	v_mfma_f32_16x16x32_bf16 v[134:137], v[4:7], v[194:197], v[134:137]
	v_mfma_f32_16x16x32_bf16 v[130:133], v[142:145], v[194:197], v[130:133]
	v_mfma_f32_16x16x32_bf16 v[118:121], v[4:7], v[202:205], v[118:121]
	v_mfma_f32_16x16x32_bf16 v[114:117], v[142:145], v[202:205], v[114:117]
	v_mfma_f32_16x16x32_bf16 v[102:105], v[4:7], v[226:229], v[102:105]
	v_mfma_f32_16x16x32_bf16 v[98:101], v[142:145], v[226:229], v[98:101]
	v_mfma_f32_16x16x32_bf16 v[84:87], v[4:7], v[234:237], v[84:87]
	v_mfma_f32_16x16x32_bf16 v[80:83], v[142:145], v[234:237], v[80:83]
	s_setprio 0
	s_setprio 1
	v_mfma_f32_16x16x32_bf16 v[126:129], v[146:149], v[190:193], v[126:129]
	v_mfma_f32_16x16x32_bf16 v[122:125], v[182:185], v[190:193], v[122:125]
	v_mfma_f32_16x16x32_bf16 v[110:113], v[146:149], v[198:201], v[110:113]
	v_mfma_f32_16x16x32_bf16 v[106:109], v[182:185], v[198:201], v[106:109]
	v_mfma_f32_16x16x32_bf16 v[92:95], v[146:149], v[222:225], v[92:95]
	v_mfma_f32_16x16x32_bf16 v[88:91], v[182:185], v[222:225], v[88:91]
	v_mfma_f32_16x16x32_bf16 v[76:79], v[146:149], v[230:233], v[76:79]
	v_mfma_f32_16x16x32_bf16 v[72:75], v[182:185], v[230:233], v[72:75]
	v_mfma_f32_16x16x32_bf16 v[126:129], v[150:153], v[194:197], v[126:129]
	v_mfma_f32_16x16x32_bf16 v[122:125], v[186:189], v[194:197], v[122:125]
	v_mfma_f32_16x16x32_bf16 v[110:113], v[150:153], v[202:205], v[110:113]
	v_mfma_f32_16x16x32_bf16 v[106:109], v[186:189], v[202:205], v[106:109]
	v_mfma_f32_16x16x32_bf16 v[92:95], v[150:153], v[226:229], v[92:95]
	v_mfma_f32_16x16x32_bf16 v[88:91], v[186:189], v[226:229], v[88:91]
	v_mfma_f32_16x16x32_bf16 v[76:79], v[150:153], v[234:237], v[76:79]
	v_mfma_f32_16x16x32_bf16 v[72:75], v[186:189], v[234:237], v[72:75]
	s_setprio 0
	s_barrier
	s_add_i32 s33, s33, s78
	s_mov_b32 m0, s33
	ds_read_b128 v[190:193], v221 offset:16384
	ds_read_b128 v[194:197], v221 offset:17408
	ds_read_b128 v[198:201], v221 offset:18432
	ds_read_b128 v[202:205], v221 offset:19456
	ds_read_b128 v[222:225], v221 offset:20480
	ds_read_b128 v[226:229], v221 offset:21504
	ds_read_b128 v[230:233], v221 offset:22528
	ds_read_b128 v[234:237], v221 offset:23552
	global_load_lds_dwordx4 v156, s[12:13]
	s_add_i32 m0, s33, 0x2000
	s_add_u32 s42, s12, 0x10000
	s_addc_u32 s43, s13, 0
	s_add_i32 s33, s35, s78
	global_load_lds_dwordx4 v160, s[12:13]
	s_mov_b32 m0, s33
	s_nop 0
	global_load_lds_dwordx4 v156, s[42:43]
	s_add_i32 m0, s33, 0x2000
	s_nop 0
	global_load_lds_dwordx4 v160, s[42:43]
	s_mov_b64 s[42:43], s[14:15]
	s_mov_b32 m0, s79
	s_nop 0
	global_load_lds_dwordx4 v154, s[14:15]
	s_mov_b32 m0, s81
	s_nop 0
	global_load_lds_dwordx4 v158, s[14:15]
	s_waitcnt vmcnt(8)
	s_waitcnt lgkmcnt(0)
	s_barrier
	s_setprio 1
	s_waitcnt lgkmcnt(0)
	v_mfma_f32_16x16x32_bf16 v[68:71], v[0:3], v[190:193], v[68:71]
	v_mfma_f32_16x16x32_bf16 v[64:67], v[138:141], v[190:193], v[64:67]
	v_mfma_f32_16x16x32_bf16 v[52:55], v[0:3], v[198:201], v[52:55]
	v_mfma_f32_16x16x32_bf16 v[48:51], v[138:141], v[198:201], v[48:51]
	v_mfma_f32_16x16x32_bf16 v[36:39], v[0:3], v[222:225], v[36:39]
	v_mfma_f32_16x16x32_bf16 v[32:35], v[138:141], v[222:225], v[32:35]
	v_mfma_f32_16x16x32_bf16 v[0:3], v[0:3], v[230:233], v[20:23]
	v_mfma_f32_16x16x32_bf16 v[68:71], v[4:7], v[194:197], v[68:71]
	v_mfma_f32_16x16x32_bf16 v[64:67], v[142:145], v[194:197], v[64:67]
	v_mfma_f32_16x16x32_bf16 v[52:55], v[4:7], v[202:205], v[52:55]
	v_mfma_f32_16x16x32_bf16 v[48:51], v[142:145], v[202:205], v[48:51]
	v_mfma_f32_16x16x32_bf16 v[36:39], v[4:7], v[226:229], v[36:39]
	v_mfma_f32_16x16x32_bf16 v[32:35], v[142:145], v[226:229], v[32:35]
	v_mfma_f32_16x16x32_bf16 v[0:3], v[4:7], v[234:237], v[0:3]
	v_mfma_f32_16x16x32_bf16 v[4:7], v[138:141], v[230:233], v[16:19]
	v_mfma_f32_16x16x32_bf16 v[4:7], v[142:145], v[234:237], v[4:7]
	s_setprio 0
	s_setprio 1
	v_mfma_f32_16x16x32_bf16 v[16:19], v[146:149], v[190:193], v[60:63]
	v_mfma_f32_16x16x32_bf16 v[60:63], v[150:153], v[194:197], v[16:19]
	v_mfma_f32_16x16x32_bf16 v[16:19], v[182:185], v[190:193], v[56:59]
	v_mfma_f32_16x16x32_bf16 v[56:59], v[186:189], v[194:197], v[16:19]
	v_mfma_f32_16x16x32_bf16 v[16:19], v[146:149], v[198:201], v[44:47]
	v_mfma_f32_16x16x32_bf16 v[44:47], v[150:153], v[202:205], v[16:19]
	v_mfma_f32_16x16x32_bf16 v[16:19], v[182:185], v[198:201], v[40:43]
	v_mfma_f32_16x16x32_bf16 v[40:43], v[186:189], v[202:205], v[16:19]
	v_mfma_f32_16x16x32_bf16 v[16:19], v[146:149], v[222:225], v[28:31]
	v_mfma_f32_16x16x32_bf16 v[28:31], v[150:153], v[226:229], v[16:19]
	v_mfma_f32_16x16x32_bf16 v[16:19], v[182:185], v[222:225], v[24:27]
	v_mfma_f32_16x16x32_bf16 v[12:15], v[146:149], v[230:233], v[12:15]
	v_mfma_f32_16x16x32_bf16 v[8:11], v[182:185], v[230:233], v[8:11]
	v_mfma_f32_16x16x32_bf16 v[24:27], v[186:189], v[226:229], v[16:19]
	v_mfma_f32_16x16x32_bf16 v[12:15], v[150:153], v[234:237], v[12:15]
	v_mfma_f32_16x16x32_bf16 v[8:11], v[186:189], v[234:237], v[8:11]
	s_setprio 0
	s_barrier
	s_add_i32 s33, 0, 0x1c000
	ds_read_b128 v[16:19], v253 offset:32768
	ds_read_b128 v[20:23], v253 offset:33792
	ds_read_b128 v[138:141], v253 offset:34816
	ds_read_b128 v[142:145], v253 offset:35840
	ds_read_b128 v[146:149], v253 offset:49152
	ds_read_b128 v[150:153], v253 offset:50176
	ds_read_b128 v[182:185], v253 offset:51200
	ds_read_b128 v[186:189], v253 offset:52224
	s_add_u32 s14, s14, 0x40000
	s_addc_u32 s15, s15, 0
	s_mov_b32 m0, s92
	ds_read_b128 v[190:193], v221 offset:32768
	ds_read_b128 v[194:197], v221 offset:33792
	ds_read_b128 v[198:201], v221 offset:34816
	ds_read_b128 v[202:205], v221 offset:35840
	ds_read_b128 v[222:225], v221 offset:36864
	ds_read_b128 v[226:229], v221 offset:37888
	ds_read_b128 v[230:233], v221 offset:38912
	ds_read_b128 v[234:237], v221 offset:39936
	global_load_lds_dwordx4 v154, s[14:15]
	s_mov_b32 m0, s93
	s_nop 0
	global_load_lds_dwordx4 v158, s[14:15]
	s_waitcnt vmcnt(8)
	s_waitcnt lgkmcnt(0)
	s_barrier
	s_setprio 1
	s_waitcnt lgkmcnt(0)
	v_mfma_f32_16x16x32_bf16 v[134:137], v[16:19], v[190:193], v[134:137]
	v_mfma_f32_16x16x32_bf16 v[130:133], v[138:141], v[190:193], v[130:133]
	v_mfma_f32_16x16x32_bf16 v[118:121], v[16:19], v[198:201], v[118:121]
	v_mfma_f32_16x16x32_bf16 v[114:117], v[138:141], v[198:201], v[114:117]
	v_mfma_f32_16x16x32_bf16 v[102:105], v[16:19], v[222:225], v[102:105]
	v_mfma_f32_16x16x32_bf16 v[98:101], v[138:141], v[222:225], v[98:101]
	v_mfma_f32_16x16x32_bf16 v[84:87], v[16:19], v[230:233], v[84:87]
	v_mfma_f32_16x16x32_bf16 v[80:83], v[138:141], v[230:233], v[80:83]
	v_mfma_f32_16x16x32_bf16 v[134:137], v[20:23], v[194:197], v[134:137]
	v_mfma_f32_16x16x32_bf16 v[130:133], v[142:145], v[194:197], v[130:133]
	v_mfma_f32_16x16x32_bf16 v[118:121], v[20:23], v[202:205], v[118:121]
	v_mfma_f32_16x16x32_bf16 v[114:117], v[142:145], v[202:205], v[114:117]
	v_mfma_f32_16x16x32_bf16 v[102:105], v[20:23], v[226:229], v[102:105]
	v_mfma_f32_16x16x32_bf16 v[98:101], v[142:145], v[226:229], v[98:101]
	v_mfma_f32_16x16x32_bf16 v[84:87], v[20:23], v[234:237], v[84:87]
	v_mfma_f32_16x16x32_bf16 v[80:83], v[142:145], v[234:237], v[80:83]
	s_setprio 0
	s_setprio 1
	v_mfma_f32_16x16x32_bf16 v[126:129], v[146:149], v[190:193], v[126:129]
	v_mfma_f32_16x16x32_bf16 v[122:125], v[182:185], v[190:193], v[122:125]
	v_mfma_f32_16x16x32_bf16 v[110:113], v[146:149], v[198:201], v[110:113]
	v_mfma_f32_16x16x32_bf16 v[106:109], v[182:185], v[198:201], v[106:109]
	v_mfma_f32_16x16x32_bf16 v[92:95], v[146:149], v[222:225], v[92:95]
	v_mfma_f32_16x16x32_bf16 v[88:91], v[182:185], v[222:225], v[88:91]
	v_mfma_f32_16x16x32_bf16 v[76:79], v[146:149], v[230:233], v[76:79]
	v_mfma_f32_16x16x32_bf16 v[72:75], v[182:185], v[230:233], v[72:75]
	v_mfma_f32_16x16x32_bf16 v[126:129], v[150:153], v[194:197], v[126:129]
	v_mfma_f32_16x16x32_bf16 v[122:125], v[186:189], v[194:197], v[122:125]
	v_mfma_f32_16x16x32_bf16 v[110:113], v[150:153], v[202:205], v[110:113]
	v_mfma_f32_16x16x32_bf16 v[106:109], v[186:189], v[202:205], v[106:109]
	v_mfma_f32_16x16x32_bf16 v[92:95], v[150:153], v[226:229], v[92:95]
	v_mfma_f32_16x16x32_bf16 v[88:91], v[186:189], v[226:229], v[88:91]
	v_mfma_f32_16x16x32_bf16 v[76:79], v[150:153], v[234:237], v[76:79]
	v_mfma_f32_16x16x32_bf16 v[72:75], v[186:189], v[234:237], v[72:75]
	s_setprio 0
	s_barrier
	s_add_i32 s14, s67, s78
	s_add_i32 m0, s14, 0xffffff80
	ds_read_b128 v[190:193], v221 offset:49152
	ds_read_b128 v[194:197], v221 offset:50176
	ds_read_b128 v[198:201], v221 offset:51200
	ds_read_b128 v[202:205], v221 offset:52224
	ds_read_b128 v[222:225], v221 offset:53248
	ds_read_b128 v[226:229], v221 offset:54272
	ds_read_b128 v[230:233], v221 offset:55296
	ds_read_b128 v[234:237], v221 offset:56320
	global_load_lds_dwordx4 v156, s[12:13] offset:128
	s_add_i32 m0, s14, 0x1f80
	s_add_i32 s14, s33, s78
	global_load_lds_dwordx4 v160, s[12:13] offset:128
	s_add_u32 s12, s12, 0x10080
	s_addc_u32 s13, s13, 0
	s_mov_b32 m0, s14
	s_nop 0
	global_load_lds_dwordx4 v156, s[12:13]
	s_add_i32 m0, s14, 0x2000
	s_nop 0
	global_load_lds_dwordx4 v160, s[12:13]
	s_add_i32 m0, s21, 0xffffff80
	s_nop 0
	global_load_lds_dwordx4 v154, s[42:43] offset:128
	s_add_i32 m0, s61, 0xffffff80
	s_nop 0
	global_load_lds_dwordx4 v158, s[42:43] offset:128
	s_waitcnt vmcnt(8)
	s_waitcnt lgkmcnt(0)
	s_barrier
	s_setprio 1
	s_waitcnt lgkmcnt(0)
	v_mfma_f32_16x16x32_bf16 v[68:71], v[16:19], v[190:193], v[68:71]
	v_mfma_f32_16x16x32_bf16 v[52:55], v[16:19], v[198:201], v[52:55]
	v_mfma_f32_16x16x32_bf16 v[36:39], v[16:19], v[222:225], v[36:39]
	v_mfma_f32_16x16x32_bf16 v[0:3], v[16:19], v[230:233], v[0:3]
	v_mfma_f32_16x16x32_bf16 v[68:71], v[20:23], v[194:197], v[68:71]
	v_mfma_f32_16x16x32_bf16 v[64:67], v[138:141], v[190:193], v[64:67]
	v_mfma_f32_16x16x32_bf16 v[52:55], v[20:23], v[202:205], v[52:55]
	v_mfma_f32_16x16x32_bf16 v[48:51], v[138:141], v[198:201], v[48:51]
	v_mfma_f32_16x16x32_bf16 v[36:39], v[20:23], v[226:229], v[36:39]
	v_mfma_f32_16x16x32_bf16 v[32:35], v[138:141], v[222:225], v[32:35]
	v_mfma_f32_16x16x32_bf16 v[20:23], v[20:23], v[234:237], v[0:3]
	v_mfma_f32_16x16x32_bf16 v[0:3], v[138:141], v[230:233], v[4:7]
	v_mfma_f32_16x16x32_bf16 v[64:67], v[142:145], v[194:197], v[64:67]
	v_mfma_f32_16x16x32_bf16 v[48:51], v[142:145], v[202:205], v[48:51]
	v_mfma_f32_16x16x32_bf16 v[32:35], v[142:145], v[226:229], v[32:35]
	v_mfma_f32_16x16x32_bf16 v[16:19], v[142:145], v[234:237], v[0:3]
	s_setprio 0
	s_setprio 1
	v_mfma_f32_16x16x32_bf16 v[0:3], v[146:149], v[190:193], v[60:63]
	v_mfma_f32_16x16x32_bf16 v[60:63], v[150:153], v[194:197], v[0:3]
	v_mfma_f32_16x16x32_bf16 v[0:3], v[182:185], v[190:193], v[56:59]
	v_mfma_f32_16x16x32_bf16 v[56:59], v[186:189], v[194:197], v[0:3]
	v_mfma_f32_16x16x32_bf16 v[0:3], v[146:149], v[198:201], v[44:47]
	v_mfma_f32_16x16x32_bf16 v[44:47], v[150:153], v[202:205], v[0:3]
	v_mfma_f32_16x16x32_bf16 v[0:3], v[182:185], v[198:201], v[40:43]
	v_mfma_f32_16x16x32_bf16 v[40:43], v[186:189], v[202:205], v[0:3]
	v_mfma_f32_16x16x32_bf16 v[0:3], v[146:149], v[222:225], v[28:31]
	v_mfma_f32_16x16x32_bf16 v[28:31], v[150:153], v[226:229], v[0:3]
	v_mfma_f32_16x16x32_bf16 v[0:3], v[182:185], v[222:225], v[24:27]
	v_mfma_f32_16x16x32_bf16 v[24:27], v[186:189], v[226:229], v[0:3]
	v_mfma_f32_16x16x32_bf16 v[0:3], v[146:149], v[230:233], v[12:15]
	v_mfma_f32_16x16x32_bf16 v[12:15], v[150:153], v[234:237], v[0:3]
	v_mfma_f32_16x16x32_bf16 v[0:3], v[182:185], v[230:233], v[8:11]
	v_mfma_f32_16x16x32_bf16 v[8:11], v[186:189], v[234:237], v[0:3]
	s_setprio 0
	s_barrier
	s_add_i32 s27, s27, 2
	s_add_u32 s4, s4, 0x100
	s_addc_u32 s5, s5, 0
	s_add_u32 s19, s19, 0x100
	s_addc_u32 s26, s26, 0
	s_cmp_gt_u32 s27, 13
	s_cbranch_scc0 .LBB0_750
	v_readlane_b32 s4, v252, 30
	v_readlane_b32 s5, v252, 31
	s_and_b64 vcc, exec, s[4:5]
	s_cbranch_vccz .LBB0_753
	s_barrier
